# replace cooperative-groups grid.sync by init flag + XCD barrier; on top of early-issue GEMM prefetch
# speedup vs baseline: 1.0152x; 1.0152x over previous
.LBB0_4:
	v_add_u32_e32 v1, 0x100, v1
	v_cmp_lt_u32_e32 vcc, s4, v1
	global_store_dword v[4:5], v3, off sc1
	s_or_b64 s[6:7], vcc, s[6:7]
	v_lshl_add_u64 v[4:5], v[4:5], 0, s[2:3]
	s_andn2_b64 exec, exec, s[6:7]
	s_cbranch_execnz .LBB0_4
	s_or_b64 exec, exec, s[6:7]
	s_waitcnt vmcnt(0)
	v_readlane_b32 s33, v243, 0
.LBB0_6:
	s_mov_b32 s2, 0
	v_writelane_b32 v243, s0, 3
	s_waitcnt lgkmcnt(0)
	s_mov_b32 s54, s96
	s_barrier
	v_writelane_b32 v243, s1, 4
	s_cmp_lg_u32 s33, 0
	s_cbranch_scc1 .Lflag_done
	s_add_u32 s8, s34, 0xd203800
	s_addc_u32 s9, s35, 0
	v_cmp_eq_u32_e32 vcc, 0, v206
	s_and_saveexec_b64 s[10:11], vcc
	v_mov_b32_e32 v2, 0x5eedb10c
	v_mov_b32_e32 v3, 0
	global_store_dword v3, v2, s[8:9] sc1
	s_or_b64 exec, exec, s[10:11]
.Lflag_done:
	s_load_dwordx4 s[8:11], s[0:1], 0x8
	s_load_dwordx2 s[44:45], s[0:1], 0x18
	s_load_dwordx2 s[38:39], s[0:1], 0x28
	s_load_dwordx16 s[16:31], s[0:1], 0x38
	s_load_dwordx2 s[40:41], s[0:1], 0x78
	s_load_dwordx2 s[42:43], s[0:1], 0x90
	v_mov_b32_e32 v14, v206
	s_mov_b32 s3, 0x10000
	v_lshl_add_u32 v2, s33, 8, v14
	v_cmp_gt_i32_e32 vcc, s3, v2
	s_and_saveexec_b64 s[0:1], vcc
	s_cbranch_execz .LBB0_14
	s_lshl_b32 s2, s54, 8
	v_cvt_f32_u32_e32 v1, s2
	v_add_u32_e32 v3, s2, v2
	v_mov_b32_e32 v4, s2
	v_cmp_gt_i32_e32 vcc, s3, v3
	v_rcp_iflag_f32_e32 v1, v1
	s_sub_i32 s6, 0, s2
	v_max_i32_e32 v5, 0x10000, v3
	v_addc_co_u32_e64 v4, s[4:5], v2, v4, vcc
	v_mul_f32_e32 v1, 0x4f7ffffe, v1
	v_cvt_u32_f32_e32 v1, v1
	v_sub_u32_e32 v4, v5, v4
	v_mul_lo_u32 v5, s6, v1
	v_mul_hi_u32 v5, v1, v5
	v_add_u32_e32 v1, v1, v5
	v_mul_hi_u32 v1, v4, v1
	v_mul_lo_u32 v5, v1, s2
	v_sub_u32_e32 v4, v4, v5
	v_add_u32_e32 v6, 1, v1
	v_cmp_le_u32_e64 s[4:5], s2, v4
	v_subrev_u32_e32 v5, s2, v4
	s_nop 0
	v_cndmask_b32_e64 v1, v1, v6, s[4:5]
	v_cndmask_b32_e64 v4, v4, v5, s[4:5]
	v_add_u32_e32 v5, 1, v1
	v_cmp_le_u32_e64 s[4:5], s2, v4
	v_mov_b32_e32 v4, v2
	s_nop 0
	v_cndmask_b32_e64 v1, v1, v5, s[4:5]
	v_addc_co_u32_e32 v1, vcc, 1, v1, vcc
	v_cmp_lt_u32_e32 vcc, 1, v1
	s_mov_b64 s[4:5], -1
	s_and_saveexec_b64 s[6:7], vcc
	s_cbranch_execz .LBB0_11
	v_and_b32_e32 v6, -2, v1
	s_lshl_b32 s3, s54, 9
	s_mov_b32 s14, s3
	s_mov_b64 s[12:13], 0
	v_mov_b32_e32 v7, 0
	v_mov_b32_e32 v8, v6
	v_mov_b64_e32 v[4:5], v[2:3]

.LBB0_132:
.LBB0_133:
	v_lshrrev_b32_e32 v1, 20, v0
	v_lshrrev_b32_e32 v0, 10, v0
	v_or_b32_e32 v0, v0, v1
	s_movk_i32 s0, 0x3ff
	v_and_or_b32 v0, v0, s0, v206
	v_cmp_eq_u32_e32 vcc, 0, v0
	s_waitcnt lgkmcnt(0)
	s_barrier
	s_and_saveexec_b64 s[0:1], vcc
	v_readlane_b32 s10, v243, 3
	v_readlane_b32 s11, v243, 4
	s_cbranch_execz .LBB0_143
	s_add_u32 s2, s34, 0xd203800
	s_addc_u32 s3, s35, 0
	v_mov_b32_e32 v2, 0
	s_mov_b32 s4, 0
.Linitpoll:
	global_load_dword v3, v2, s[2:3] sc1
	s_waitcnt vmcnt(0)
	v_cmp_eq_u32_e32 vcc, 0x5eedb10c, v3
	s_nop 1
	s_cbranch_vccnz .Linitok
	s_sleep 1
	s_add_i32 s4, s4, 1
	s_cmp_lt_u32 s4, 0x10000
	s_cbranch_scc1 .Linitpoll
.Linitok:
.LBB0_143:
	s_or_b64 exec, exec, s[0:1]
	s_add_u32 s0, s34, 0xd200000
	s_barrier
	s_getreg_b32 s2, hwreg(HW_REG_XCC_ID, 0, 4)
	s_addc_u32 s1, s35, 0
	s_and_b32 s7, s2, 15
	s_lshl_b32 s6, s7, 6
	s_mov_b32 s77, 0
	s_mov_b64 s[2:3], exec
	v_readlane_b32 s4, v243, 1
	v_readlane_b32 s5, v243, 2
	s_and_b64 s[4:5], s[2:3], s[4:5]
	s_mov_b64 exec, s[4:5]
	s_cbranch_execz .LBB0_146
	s_mov_b64 s[4:5], exec
	v_mbcnt_lo_u32_b32 v0, s4, 0
	v_mbcnt_hi_u32_b32 v0, s5, v0
	v_cmp_eq_u32_e32 vcc, 0, v0
	s_and_b64 s[8:9], exec, vcc
	s_mov_b64 exec, s[8:9]
	s_cbranch_execz .LBB0_146
	s_lshl_b32 s8, s6, 2
	s_bcnt1_i32_b64 s4, s[4:5]
	v_mov_b32_e32 v0, s8
	v_mov_b32_e32 v1, s4
	global_atomic_add v0, v1, s[0:1] offset:1024
.LBB0_146:
	s_or_b64 exec, exec, s[2:3]
	s_load_dword s3, s[10:11], 0xa0
	s_mul_i32 s2, s97, s96
	v_mbcnt_lo_u32_b32 v0, -1, 0
	v_mbcnt_hi_u32_b32 v209, -1, v0
	v_and_b32_e32 v0, 64, v209
	s_waitcnt lgkmcnt(0)
	s_mul_i32 s2, s2, s3
	v_writelane_b32 v243, s2, 5
	s_add_u32 s2, s34, 0xd200200
	s_addc_u32 s3, s35, 0
	v_writelane_b32 v243, s2, 6
	v_mov_b32_e32 v1, 0
	s_movk_i32 s20, 0x3000
	v_writelane_b32 v243, s3, 7
	s_add_u32 s2, s34, 0xd200400
	s_addc_u32 s3, s35, 0
	v_writelane_b32 v243, s2, 8
	s_mov_b32 s27, 0xd400000
	v_mov_b32_e32 v207, 1
	v_writelane_b32 v243, s3, 9
	s_add_u32 s2, s34, 0xd200500
	s_addc_u32 s3, s35, 0
	v_writelane_b32 v243, s2, 10
	s_movk_i32 s21, 0x90
	v_mov_b32_e32 v208, 0x358637bd
	v_writelane_b32 v243, s3, 11
	s_add_u32 s2, s34, 0xd200600
	s_addc_u32 s3, s35, 0
	v_writelane_b32 v243, s2, 12
	v_add_u32_e32 v210, 64, v0
	v_xor_b32_e32 v211, 32, v209
	v_writelane_b32 v243, s3, 13
	s_add_u32 s2, s34, 0xd200700
	s_addc_u32 s3, s35, 0
	v_writelane_b32 v243, s2, 14
	v_xor_b32_e32 v212, 16, v209
	v_xor_b32_e32 v213, 8, v209
	v_writelane_b32 v243, s3, 15
	s_add_u32 s2, s34, 0xd200800
	s_addc_u32 s3, s35, 0
	v_writelane_b32 v243, s2, 16
	v_xor_b32_e32 v214, 4, v209
	v_xor_b32_e32 v215, 2, v209
	v_writelane_b32 v243, s3, 17
	s_add_u32 s2, s34, 0xd200900
	s_addc_u32 s3, s35, 0
	v_writelane_b32 v243, s2, 18
	v_xor_b32_e32 v216, 1, v209
	v_mov_b32_e32 v217, 2
	v_writelane_b32 v243, s3, 19
	s_add_u32 s2, s34, 0xd200a00
	s_addc_u32 s3, s35, 0
	v_writelane_b32 v243, s2, 20
	v_mov_b64_e32 v[178:179], 0xf500000
	v_bfrev_b32_e32 v218, 32
	v_writelane_b32 v243, s3, 21
	s_add_u32 s2, s34, 0xd200b00
	s_addc_u32 s3, s35, 0
	v_writelane_b32 v243, s2, 22
	v_bfrev_b32_e32 v219, 64
	v_mov_b32_e32 v220, 0xff800000
	v_writelane_b32 v243, s3, 23
	s_add_u32 s2, s34, 0xd200c00
	s_addc_u32 s3, s35, 0
	v_writelane_b32 v243, s2, 24
	v_mov_b32_e32 v221, 0x80
	v_mov_b32_e32 v222, 0x200
	v_writelane_b32 v243, s3, 25
	s_add_u32 s2, s34, 0xd200d00
	s_addc_u32 s3, s35, 0
	v_writelane_b32 v243, s2, 26
	v_mov_b32_e32 v223, 0x2000
	v_mov_b32_e32 v224, 0x461c4000
	v_writelane_b32 v243, s3, 27
	s_add_u32 s2, s34, 0xd200e00
	s_addc_u32 s3, s35, 0
	v_writelane_b32 v243, s2, 28
	v_mov_b32_e32 v225, 0x63
	s_mov_b32 s26, 0x10000
	v_writelane_b32 v243, s3, 29
	s_add_u32 s2, s34, 0xd200f00
	s_addc_u32 s3, s35, 0
	v_writelane_b32 v243, s2, 30
	s_mov_b32 s78, 0x20000
	s_mov_b32 s79, 0x30000
	v_writelane_b32 v243, s3, 31
	s_add_u32 s2, s34, 0xd201000
	s_addc_u32 s3, s35, 0
	v_writelane_b32 v243, s2, 32
	s_mov_b32 s33, 0x50000
	s_mov_b32 s80, 0x60000
	v_writelane_b32 v243, s3, 33
	s_add_u32 s2, s34, 0xd201100
	s_addc_u32 s3, s35, 0
	v_writelane_b32 v243, s2, 34
	s_mov_b32 s81, 0xd410000
	s_mov_b32 s82, 0xd420000
	v_writelane_b32 v243, s3, 35
	s_add_u32 s2, s34, 0xd201200
	s_addc_u32 s3, s35, 0
	v_writelane_b32 v243, s2, 36
	s_mov_b32 s83, 0xd430000
	s_mov_b32 s84, 0x800000
	v_writelane_b32 v243, s3, 37
	s_add_u32 s2, s34, 0xd201300
	s_addc_u32 s3, s35, 0
	v_writelane_b32 v243, s2, 38
	s_cmp_eq_u32 s7, 15
	s_mov_b32 s85, 0xff800000
	v_writelane_b32 v243, s3, 39
	s_cselect_b64 s[2:3], -1, 0
	v_writelane_b32 v243, s2, 40
	s_cmp_eq_u32 s7, 14
	s_mov_b32 s86, 0x3e38aa3b
	v_writelane_b32 v243, s3, 41
	s_cselect_b64 s[2:3], -1, 0
	v_writelane_b32 v243, s2, 42
	s_cmp_eq_u32 s7, 13
	s_mov_b32 s87, 0xc400000
	v_writelane_b32 v243, s3, 43
	s_cselect_b64 s[2:3], -1, 0
	v_writelane_b32 v243, s2, 44
	s_cmp_eq_u32 s7, 12
	s_mov_b32 s88, 0xc420000
	v_writelane_b32 v243, s3, 45
	s_cselect_b64 s[2:3], -1, 0
	v_writelane_b32 v243, s2, 46
	s_cmp_eq_u32 s7, 11
	s_mov_b32 s89, 0xc440000
	v_writelane_b32 v243, s3, 47
	s_cselect_b64 s[2:3], -1, 0
	v_writelane_b32 v243, s2, 48
	s_cmp_eq_u32 s7, 10
	s_mov_b32 s90, 0xc460000
	v_writelane_b32 v243, s3, 49
	s_cselect_b64 s[2:3], -1, 0
	v_writelane_b32 v243, s2, 50
	s_cmp_eq_u32 s7, 9
	s_mov_b32 s91, 0xc480000
	v_writelane_b32 v243, s3, 51
	s_cselect_b64 s[2:3], -1, 0
	v_writelane_b32 v243, s2, 52
	s_cmp_eq_u32 s7, 8
	s_mov_b32 s92, 0xc4a0000
	v_writelane_b32 v243, s3, 53
	s_cselect_b64 s[2:3], -1, 0
	v_writelane_b32 v243, s2, 54
	s_cmp_eq_u32 s7, 7
	s_mov_b32 s93, 0xc4c0000
	v_writelane_b32 v243, s3, 55
	s_cselect_b64 s[2:3], -1, 0
	v_writelane_b32 v243, s2, 56
	s_cmp_eq_u32 s7, 6
	s_mov_b32 s94, 0xc4e0000
	v_writelane_b32 v243, s3, 57
	s_cselect_b64 s[2:3], -1, 0
	v_writelane_b32 v243, s2, 58
	s_cmp_eq_u32 s7, 5
	s_mov_b32 s95, 0xc00000
	v_writelane_b32 v243, s3, 59
	s_cselect_b64 s[2:3], -1, 0
	v_writelane_b32 v243, s2, 60
	s_cmp_eq_u32 s7, 4
	s_movk_i32 s96, 0x1bff
	v_writelane_b32 v243, s3, 61
	s_cselect_b64 s[2:3], -1, 0
	v_writelane_b32 v243, s2, 62
	s_cmp_eq_u32 s7, 3
	s_mov_b32 s97, 0xd080000
	v_writelane_b32 v243, s3, 63
	s_cselect_b64 s[2:3], -1, 0
	v_writelane_b32 v242, s2, 0
	s_cmp_eq_u32 s7, 2
	s_mov_b32 s12, 0
	v_writelane_b32 v242, s3, 1
	s_cselect_b64 s[2:3], -1, 0
	v_writelane_b32 v242, s2, 2
	s_cmp_eq_u32 s7, 1
	s_mov_b64 s[24:25], 0x800
	v_writelane_b32 v242, s3, 3
	s_cselect_b64 s[2:3], -1, 0
	v_writelane_b32 v242, s2, 4
	s_cmp_eq_u32 s7, 0
	s_mov_b64 s[28:29], 0x80
	v_writelane_b32 v242, s3, 5
	s_cselect_b64 s[2:3], -1, 0
	v_writelane_b32 v242, s2, 6
	s_mov_b64 s[30:31], 0x20000
	s_nop 0
	v_writelane_b32 v242, s3, 7
	s_lshl_b32 s2, s6, 2
	s_add_u32 s0, s0, s2
	s_addc_u32 s1, s1, 0
	s_add_u32 s2, s0, 0x1400
	s_addc_u32 s3, s1, 0
	v_writelane_b32 v242, s2, 8
	s_add_u32 s0, s0, 0x2400
	s_addc_u32 s1, s1, 0
	v_writelane_b32 v242, s3, 9
	v_writelane_b32 v242, s0, 10
	s_nop 1
	v_writelane_b32 v242, s1, 11
	s_add_u32 s0, s34, 0xd203400
	s_addc_u32 s1, s35, 0
	v_writelane_b32 v242, s0, 12
	s_nop 1
	v_writelane_b32 v242, s1, 13
	s_add_u32 s0, s34, 0xd203500
	s_addc_u32 s1, s35, 0
	v_writelane_b32 v242, s0, 14
	s_nop 1
	v_writelane_b32 v242, s1, 15
	s_mov_b32 s1, 0x400000
	s_mov_b32 s0, 0x40000
.Lgs0_217:
	s_waitcnt vmcnt(0)
	s_waitcnt lgkmcnt(0)
	s_barrier
	s_mov_b64 s[18:19], exec
	v_readlane_b32 s2, v243, 1
	v_readlane_b32 s3, v243, 2
	s_and_b64 s[2:3], s[18:19], s[2:3]
	s_mov_b64 exec, s[2:3]
	s_cbranch_execz .Lgs0_269
	s_waitcnt vmcnt(0) expcnt(0) lgkmcnt(0)
	ds_read_b32 v3, v1 offset:55296
	ds_read_b32 v2, v1 offset:55300
	s_waitcnt lgkmcnt(1)
	v_cmp_ne_u32_e32 vcc, 0, v3
	s_cbranch_vccnz .Lgs0_233
	s_mov_b32 s4, 1
	s_branch .Lgs0_221

.Lgs0_269:
	s_or_b64 exec, exec, s[18:19]
	s_waitcnt lgkmcnt(0)
	s_barrier
	s_branch .LBB0_149
